# grid barrier: every workgroup starts an L2 writeback before its arrival so the last arriver's flush is short
# speedup vs baseline: 1.0306x; 1.0306x over previous
.LBB0_44:
	s_mov_b64 s[4:5], exec
	v_mbcnt_lo_u32_b32 v1, s4, 0
	s_add_u32 s10, s48, 0x1000
	v_mbcnt_hi_u32_b32 v1, s5, v1
	s_addc_u32 s11, s49, 0
	s_lshl_b32 s15, s2, 6
	v_cmp_eq_u32_e32 vcc, 0, v1
	s_and_saveexec_b64 s[6:7], vcc
	s_cbranch_execz .LBB0_46
	buffer_wbl2 sc1
	s_waitcnt vmcnt(0)
	s_add_i32 s16, s15, 0x500
	s_lshl_b64 s[18:19], s[16:17], 2
	s_add_u32 s18, s10, s18
	s_addc_u32 s19, s11, s19
	s_bcnt1_i32_b64 s2, s[4:5]
	v_mov_b32_e32 v3, s2
	global_atomic_add v3, v97, v3, s[18:19] sc0
